# v27 plus MLA flash loop: causal-mask operand set-up moved into the rarely taken masking branch
# speedup vs baseline: 1.0070x; 1.0024x over previous
; #define MFMA16(a, b, c) __builtin_amdgcn_mfma_f32_16x16x32_bf16((a), (b), (c), 0, 0, 0)
;     ...
;         for (int sb = 0; sb < 2; ++sb)
; #pragma unroll
;             for (int t = 0; t < 2; ++t) s[sb][t] = (f32x4){0.f, 0.f, 0.f, 0.f};
;         if (PRB < 2) {
;         {
;     ...
;             bf16x8 kq[3]; kq[0] = FL_RK(0); kq[1] = FL_RK(1);
; #pragma unroll
;             for (int e = 0; e < 2 * NKS; ++e) { if (e + 2 < 2 * NKS) kq[(e + 2) % 3] = FL_RK(e + 2);
;                 s[0][e / NKS] = MFMA16(kq[e % 3], qf[0][e % NKS], s[0][e / NKS]); s[1][e / NKS] = MFMA16(kq[e % 3], qf[1][e % NKS], s[1][e / NKS]);
;                 }
;     ...
;         }
;         }
;         const bool need_mask = PRB == 0 && (MODE == 1 || key0 < 128 || key0 + 31 > qbase);
;         bf16x8 pf[2];
; #pragma unroll
;         for (int sb = 0; sb < 2; ++sb) {
;             const int qrow = qbase + 16 * sb + c16;
;             if (need_mask) {
; #pragma unroll
;                 for (int t = 0; t < 2; ++t)
; #pragma unroll
;                     for (int r = 0; r < 4; ++r) { const int k = key0 + 16 * t + 4 * g + r;
;                         bool vis = k >= PADR && k <= qrow; if (MODE == 1) vis = vis && (qrow - k < 128 || k < 128);
;                         if (!vis) s[sb][t][r] = -1e30f; }
.LBB0_786:
	v_add_u32_e32 v226, v201, v186
	ds_read_b128 v[154:157], v226
	ds_read_b128 v[158:161], v226 offset:64
	ds_read_b128 v[162:165], v226 offset:128
	ds_read_b128 v[214:217], v226 offset:192
	ds_read_b128 v[218:221], v226 offset:320
	s_waitcnt lgkmcnt(4)
	v_mfma_f32_16x16x32_bf16 v[166:169], v[154:157], v[66:69], 0
	ds_read_b128 v[222:225], v226 offset:6592
	s_add_i32 s9, s70, s8
	s_add_i32 s12, s9, 0xffffff40
	v_mfma_f32_16x16x32_bf16 v[154:157], v[154:157], v[90:93], 0
	s_cmpk_lt_i32 s12, 0x80
	s_cselect_b64 s[12:13], -1, 0
	s_addk_i32 s9, 0xff5f
	s_waitcnt lgkmcnt(4)
	v_mfma_f32_16x16x32_bf16 v[166:169], v[158:161], v[70:73], v[166:169]
	s_cmp_gt_i32 s9, s44
	s_cselect_b64 s[14:15], -1, 0
	s_or_b64 s[14:15], s[12:13], s[14:15]
	v_mfma_f32_16x16x32_bf16 v[154:157], v[158:161], v[94:97], v[154:157]
	ds_read_b128 v[158:161], v226 offset:256
	s_andn2_b64 vcc, exec, s[14:15]
	s_waitcnt lgkmcnt(4)
	v_mfma_f32_16x16x32_bf16 v[166:169], v[162:165], v[74:77], v[166:169]
	v_mfma_f32_16x16x32_bf16 v[154:157], v[162:165], v[98:101], v[154:157]
	s_waitcnt lgkmcnt(3)
	v_mfma_f32_16x16x32_bf16 v[162:165], v[214:217], v[78:81], v[166:169]
	v_mfma_f32_16x16x32_bf16 v[154:157], v[214:217], v[102:105], v[154:157]
	s_nop 3
	ds_read_b128 v[166:169], v226 offset:6400
	ds_read_b128 v[214:217], v226 offset:6528
	s_waitcnt lgkmcnt(2)
	v_mfma_f32_16x16x32_bf16 v[162:165], v[158:161], v[82:85], v[162:165]
	v_mfma_f32_16x16x32_bf16 v[154:157], v[158:161], v[106:109], v[154:157]
	ds_read_b128 v[158:161], v226 offset:6464
	v_mfma_f32_16x16x32_bf16 v[162:165], v[218:221], v[86:89], v[162:165]
	v_mfma_f32_16x16x32_bf16 v[154:157], v[218:221], v[110:113], v[154:157]
	s_waitcnt lgkmcnt(2)
	v_mfma_f32_16x16x32_bf16 v[218:221], v[166:169], v[66:69], 0
	v_mfma_f32_16x16x32_bf16 v[166:169], v[166:169], v[90:93], 0
	s_waitcnt lgkmcnt(0)
	v_mfma_f32_16x16x32_bf16 v[218:221], v[158:161], v[70:73], v[218:221]
	v_mfma_f32_16x16x32_bf16 v[158:161], v[158:161], v[94:97], v[166:169]
	s_nop 4
	ds_read_b128 v[166:169], v226 offset:6656
	v_mfma_f32_16x16x32_bf16 v[218:221], v[214:217], v[74:77], v[218:221]
	v_mfma_f32_16x16x32_bf16 v[158:161], v[214:217], v[98:101], v[158:161]
	ds_read_b128 v[214:217], v226 offset:6720
	v_mfma_f32_16x16x32_bf16 v[218:221], v[222:225], v[78:81], v[218:221]
	v_mfma_f32_16x16x32_bf16 v[158:161], v[222:225], v[102:105], v[158:161]
	s_waitcnt lgkmcnt(1)
	v_mfma_f32_16x16x32_bf16 v[218:221], v[166:169], v[82:85], v[218:221]
	v_mfma_f32_16x16x32_bf16 v[158:161], v[166:169], v[106:109], v[158:161]
	s_waitcnt lgkmcnt(0)
	v_mfma_f32_16x16x32_bf16 v[166:169], v[214:217], v[86:89], v[218:221]
	v_mfma_f32_16x16x32_bf16 v[158:161], v[214:217], v[110:113], v[158:161]
	s_not_b64 s[12:13], s[14:15]
	s_nop 4
	s_cbranch_vccnz .LBB0_788
	v_add_u32_e32 v214, s8, v202
	v_add_u32_e32 v219, 0xffffff40, v214
	v_add_u32_e32 v225, 0xffffff42, v214
	v_add_u32_e32 v224, 0xffffff43, v214
	v_add_u32_e32 v223, 0xffffff50, v214
	v_add_u32_e32 v222, 0xffffff51, v214
	v_add_u32_e32 v221, 0xffffff52, v214
	v_add_u32_e32 v220, 0xffffff53, v214
	v_cmp_lt_i32_e64 s[16:17], s94, v219
	v_cmp_lt_i32_e64 s[14:15], s62, v219
	v_cmp_le_i32_e64 s[30:31], v219, v184
	v_cmp_lt_i32_e64 s[28:29], s94, v225
	v_cmp_lt_i32_e64 s[26:27], s94, v224
	v_cmp_lt_i32_e64 s[24:25], s94, v223
	v_cmp_lt_i32_e64 s[22:23], s94, v222
	v_cmp_lt_i32_e64 s[20:21], s94, v221
	v_cmp_lt_i32_e64 s[18:19], s94, v220
	v_mov_b32_e32 v214, s93
	s_and_b64 vcc, s[16:17], s[30:31]
	v_cndmask_b32_e32 v162, v214, v162, vcc
	v_cmp_lt_i32_e32 vcc, v219, v184
	s_and_b64 vcc, s[14:15], vcc
	s_nop 0
	v_cndmask_b32_e32 v163, v233, v163, vcc
	v_cmp_le_i32_e32 vcc, v225, v184
	s_and_b64 vcc, s[28:29], vcc
	s_nop 0
	v_cndmask_b32_e32 v164, v233, v164, vcc
	v_cmp_le_i32_e32 vcc, v224, v184
	s_and_b64 vcc, s[26:27], vcc
	s_nop 0
	v_cndmask_b32_e32 v165, v233, v165, vcc
	v_cmp_le_i32_e32 vcc, v223, v184
	s_and_b64 vcc, s[24:25], vcc
	s_nop 0
	v_cndmask_b32_e32 v166, v214, v166, vcc
	v_cmp_le_i32_e32 vcc, v222, v184
	s_and_b64 vcc, s[22:23], vcc
	s_nop 0
	v_cndmask_b32_e32 v167, v233, v167, vcc
	v_cmp_le_i32_e32 vcc, v221, v184
	s_and_b64 vcc, s[20:21], vcc
	s_nop 0
	v_cndmask_b32_e32 v168, v233, v168, vcc
	v_cmp_le_i32_e32 vcc, v220, v184
	s_and_b64 vcc, s[18:19], vcc
	s_nop 0
	v_cndmask_b32_e32 v169, v233, v169, vcc

; #define MFMA16(a, b, c) __builtin_amdgcn_mfma_f32_16x16x32_bf16((a), (b), (c), 0, 0, 0)
;     ...
;         for (int sb = 0; sb < 2; ++sb)
; #pragma unroll
;             for (int t = 0; t < 2; ++t) s[sb][t] = (f32x4){0.f, 0.f, 0.f, 0.f};
;         if (PRB < 2) {
;         {
;     ...
;             bf16x8 kq[3]; kq[0] = FL_RK(0); kq[1] = FL_RK(1);
; #pragma unroll
;             for (int e = 0; e < 2 * NKS; ++e) { if (e + 2 < 2 * NKS) kq[(e + 2) % 3] = FL_RK(e + 2);
;                 s[0][e / NKS] = MFMA16(kq[e % 3], qf[0][e % NKS], s[0][e / NKS]); s[1][e / NKS] = MFMA16(kq[e % 3], qf[1][e % NKS], s[1][e / NKS]);
;                 }
;     ...
;         }
;         }
;         const bool need_mask = PRB == 0 && (MODE == 1 || key0 < 128 || key0 + 31 > qbase);
;         bf16x8 pf[2];
; #pragma unroll
;         for (int sb = 0; sb < 2; ++sb) {
;             const int qrow = qbase + 16 * sb + c16;
;             if (need_mask) {
; #pragma unroll
;                 for (int t = 0; t < 2; ++t)
; #pragma unroll
;                     for (int r = 0; r < 4; ++r) { const int k = key0 + 16 * t + 4 * g + r;
;                         bool vis = k >= PADR && k <= qrow; if (MODE == 1) vis = vis && (qrow - k < 128 || k < 128);
;                         if (!vis) s[sb][t][r] = -1e30f; }
.LBB0_798:
	v_add_u32_e32 v226, v201, v186
	ds_read_b128 v[154:157], v226 offset:44032
	ds_read_b128 v[158:161], v226 offset:44096
	ds_read_b128 v[162:165], v226 offset:44160
	ds_read_b128 v[214:217], v226 offset:44224
	ds_read_b128 v[218:221], v226 offset:44352
	s_waitcnt lgkmcnt(4)
	v_mfma_f32_16x16x32_bf16 v[166:169], v[154:157], v[66:69], 0
	ds_read_b128 v[222:225], v226 offset:50624
	s_add_i32 s9, s70, s8
	s_add_i32 s12, s9, 0xffffff80
	v_mfma_f32_16x16x32_bf16 v[154:157], v[154:157], v[90:93], 0
	s_cmpk_lt_i32 s12, 0x80
	s_cselect_b64 s[12:13], -1, 0
	s_addk_i32 s9, 0xff9f
	s_waitcnt lgkmcnt(4)
	v_mfma_f32_16x16x32_bf16 v[166:169], v[158:161], v[70:73], v[166:169]
	s_cmp_gt_i32 s9, s44
	s_cselect_b64 s[14:15], -1, 0
	s_or_b64 s[14:15], s[12:13], s[14:15]
	v_mfma_f32_16x16x32_bf16 v[154:157], v[158:161], v[94:97], v[154:157]
	ds_read_b128 v[158:161], v226 offset:44288
	s_andn2_b64 vcc, exec, s[14:15]
	s_waitcnt lgkmcnt(4)
	v_mfma_f32_16x16x32_bf16 v[166:169], v[162:165], v[74:77], v[166:169]
	v_mfma_f32_16x16x32_bf16 v[154:157], v[162:165], v[98:101], v[154:157]
	s_waitcnt lgkmcnt(3)
	v_mfma_f32_16x16x32_bf16 v[162:165], v[214:217], v[78:81], v[166:169]
	v_mfma_f32_16x16x32_bf16 v[154:157], v[214:217], v[102:105], v[154:157]
	s_nop 3
	ds_read_b128 v[166:169], v226 offset:50432
	ds_read_b128 v[214:217], v226 offset:50560
	s_waitcnt lgkmcnt(2)
	v_mfma_f32_16x16x32_bf16 v[162:165], v[158:161], v[82:85], v[162:165]
	v_mfma_f32_16x16x32_bf16 v[154:157], v[158:161], v[106:109], v[154:157]
	ds_read_b128 v[158:161], v226 offset:50496
	v_mfma_f32_16x16x32_bf16 v[162:165], v[218:221], v[86:89], v[162:165]
	v_mfma_f32_16x16x32_bf16 v[154:157], v[218:221], v[110:113], v[154:157]
	s_waitcnt lgkmcnt(2)
	v_mfma_f32_16x16x32_bf16 v[218:221], v[166:169], v[66:69], 0
	v_mfma_f32_16x16x32_bf16 v[166:169], v[166:169], v[90:93], 0
	s_waitcnt lgkmcnt(0)
	v_mfma_f32_16x16x32_bf16 v[218:221], v[158:161], v[70:73], v[218:221]
	v_mfma_f32_16x16x32_bf16 v[158:161], v[158:161], v[94:97], v[166:169]
	s_nop 4
	ds_read_b128 v[166:169], v226 offset:50688
	v_mfma_f32_16x16x32_bf16 v[218:221], v[214:217], v[74:77], v[218:221]
	v_mfma_f32_16x16x32_bf16 v[158:161], v[214:217], v[98:101], v[158:161]
	ds_read_b128 v[214:217], v226 offset:50752
	v_mfma_f32_16x16x32_bf16 v[218:221], v[222:225], v[78:81], v[218:221]
	v_mfma_f32_16x16x32_bf16 v[158:161], v[222:225], v[102:105], v[158:161]
	s_waitcnt lgkmcnt(1)
	v_mfma_f32_16x16x32_bf16 v[218:221], v[166:169], v[82:85], v[218:221]
	v_mfma_f32_16x16x32_bf16 v[158:161], v[166:169], v[106:109], v[158:161]
	s_waitcnt lgkmcnt(0)
	v_mfma_f32_16x16x32_bf16 v[166:169], v[214:217], v[86:89], v[218:221]
	v_mfma_f32_16x16x32_bf16 v[158:161], v[214:217], v[110:113], v[158:161]
	s_not_b64 s[12:13], s[14:15]
	s_nop 4
	s_cbranch_vccnz .LBB0_800
	v_add_u32_e32 v214, s8, v202
	v_add_u32_e32 v219, 0xffffff80, v214
	v_add_u32_e32 v225, 0xffffff82, v214
	v_add_u32_e32 v224, 0xffffff83, v214
	v_add_u32_e32 v223, 0xffffff90, v214
	v_add_u32_e32 v222, 0xffffff91, v214
	v_add_u32_e32 v221, 0xffffff92, v214
	v_add_u32_e32 v220, 0xffffff93, v214
	v_cmp_lt_i32_e64 s[16:17], s94, v219
	v_cmp_lt_i32_e64 s[14:15], s62, v219
	v_cmp_le_i32_e64 s[30:31], v219, v184
	v_cmp_lt_i32_e64 s[28:29], s94, v225
	v_cmp_lt_i32_e64 s[26:27], s94, v224
	v_cmp_lt_i32_e64 s[24:25], s94, v223
	v_cmp_lt_i32_e64 s[22:23], s94, v222
	v_cmp_lt_i32_e64 s[20:21], s94, v221
	v_cmp_lt_i32_e64 s[18:19], s94, v220
	v_mov_b32_e32 v214, s93
	s_and_b64 vcc, s[16:17], s[30:31]
	v_cndmask_b32_e32 v162, v214, v162, vcc
	v_cmp_lt_i32_e32 vcc, v219, v184
	s_and_b64 vcc, s[14:15], vcc
	s_nop 0
	v_cndmask_b32_e32 v163, v233, v163, vcc
	v_cmp_le_i32_e32 vcc, v225, v184
	s_and_b64 vcc, s[28:29], vcc
	s_nop 0
	v_cndmask_b32_e32 v164, v233, v164, vcc
	v_cmp_le_i32_e32 vcc, v224, v184
	s_and_b64 vcc, s[26:27], vcc
	s_nop 0
	v_cndmask_b32_e32 v165, v233, v165, vcc
	v_cmp_le_i32_e32 vcc, v223, v184
	s_and_b64 vcc, s[24:25], vcc
	s_nop 0
	v_cndmask_b32_e32 v166, v214, v166, vcc
	v_cmp_le_i32_e32 vcc, v222, v184
	s_and_b64 vcc, s[22:23], vcc
	s_nop 0
	v_cndmask_b32_e32 v167, v233, v167, vcc
	v_cmp_le_i32_e32 vcc, v221, v184
	s_and_b64 vcc, s[20:21], vcc
	s_nop 0
	v_cndmask_b32_e32 v168, v233, v168, vcc
	v_cmp_le_i32_e32 vcc, v220, v184
	s_and_b64 vcc, s[18:19], vcc
	s_nop 0
	v_cndmask_b32_e32 v169, v233, v169, vcc
